# GQA loop: next K/V tile loads issued at the bottom of the previous iteration (right after the ds_writes free the staging registers, before the LDS wait and barrier) instead of after the barrier and ds
# speedup vs baseline: 1.0094x; 1.0094x over previous
.LBB0_753:
	s_and_b64 vcc, exec, s[0:1]
	s_cbranch_vccz .LBB0_757
	s_waitcnt vmcnt(18)
	v_mov_b32_e32 v22, v179
	v_mov_b64_e32 v[8:9], s[66:67]
	v_and_b32_e32 v105, 31, v22
	v_ashrrev_i32_e32 v0, 1, v22
	v_and_b32_e32 v0, 0xffffffe0, v0
	v_or_b32_e32 v1, s4, v105
	v_add_u32_e32 v0, v1, v0
	v_bfe_u32 v23, v22, 5, 1
	v_mad_i64_i32 v[0:1], s[0:1], v0, s43, v[8:9]
	s_lshl_b32 s96, s3, 1
	v_lshl_add_u64 v[0:1], v[0:1], 0, s[96:97]
	v_lshlrev_b32_e32 v176, 4, v23
	v_lshl_add_u64 v[0:1], v[0:1], 0, v[176:177]
	v_ashrrev_i32_e32 v107, 3, v22
	s_mov_b32 s7, s95
	global_load_dwordx4 v[76:79], v[0:1], off offset:1536
	global_load_dwordx4 v[72:75], v[0:1], off offset:1568
	global_load_dwordx4 v[68:71], v[0:1], off offset:1600
	global_load_dwordx4 v[64:67], v[0:1], off offset:1632
	v_add_u32_e32 v0, s7, v107
	v_mad_i64_i32 v[0:1], s[0:1], v0, s43, v[8:9]
	s_lshl_b32 s96, s6, 1
	v_lshlrev_b32_e32 v2, 4, v22
	v_lshl_add_u64 v[0:1], v[0:1], 0, s[96:97]
	v_and_b32_e32 v98, 0x70, v2
	v_mov_b32_e32 v99, v177
	v_lshl_add_u64 v[0:1], v[0:1], 0, v[98:99]
	global_load_dwordx4 v[0:3], v[0:1], off
	s_movk_i32 s6, 0x2200
	v_mad_i64_i32 v[4:5], s[0:1], v107, s6, v[96:97]
	v_lshl_add_u64 v[4:5], v[4:5], 0, v[98:99]
	s_waitcnt vmcnt(20)
	v_add_u32_e32 v24, 0x100, v22
	global_load_dwordx4 v[4:7], v[4:5], off
	v_ashrrev_i32_e32 v108, 3, v24
	v_add_u32_e32 v10, s7, v108
	v_mad_i64_i32 v[8:9], s[0:1], v10, s43, v[8:9]
	v_lshl_add_u64 v[8:9], v[8:9], 0, s[96:97]
	v_lshl_add_u64 v[8:9], v[8:9], 0, v[98:99]
	global_load_dwordx4 v[8:11], v[8:9], off
	v_mad_i64_i32 v[12:13], s[0:1], v108, s6, v[96:97]
	v_lshl_add_u64 v[12:13], v[12:13], 0, v[98:99]
	global_load_dwordx4 v[12:15], v[12:13], off
	v_mad_u64_u32 v[20:21], s[0:1], v107, s42, v[98:99]
	v_mad_i64_i32 v[16:17], s[0:1], v107, s6, 0
	v_mad_i64_i32 v[18:19], s[0:1], v108, s6, 0
	v_or_b32_e32 v16, v16, v98
	v_or_b32_e32 v18, v18, v98
	v_lshlrev_b32_e32 v106, 3, v23
	v_lshlrev_b32_e32 v104, 2, v23
	v_add_u32_e32 v109, 64, v108
	v_add_u32_e32 v110, 64, v107
	s_movk_i32 s8, 0xff00
	s_movk_i32 s9, 0x4800
	s_mov_b64 s[10:11], 0x80
	v_readlane_b32 s12, v255, 5
	s_waitcnt vmcnt(3)
	ds_write_b128 v20, v[0:3]
	v_and_b32_e32 v0, -8, v22
	v_sub_u32_e32 v0, v20, v0
	v_add_u32_e32 v0, 0x4800, v0
	s_waitcnt vmcnt(2)
	ds_write2_b64 v0, v[4:5], v[6:7] offset1:1
	v_mad_u64_u32 v[0:1], s[0:1], v108, s42, v[98:99]
	s_add_u32 s0, s66, s96
	s_addc_u32 s1, s67, 0
	v_lshl_add_u64 v[96:97], s[0:1], 0, v[98:99]
	v_readlane_b32 s0, v255, 6
	v_and_b32_e32 v1, -8, v24
	s_add_i32 s0, s0, s5
	v_readlane_b32 s1, v254, 12
	s_waitcnt vmcnt(1)
	ds_write_b128 v0, v[8:11]
	v_sub_u32_e32 v0, v0, v1
	s_add_u32 s0, s1, s0
	v_readlane_b32 s1, v254, 13
	v_add_u32_e32 v0, 0x4800, v0
	s_addc_u32 s1, s1, 0
	v_mov_b32_e32 v99, 0
	s_waitcnt vmcnt(0)
	ds_write2_b64 v0, v[12:13], v[14:15] offset1:1
	v_lshl_add_u64 v[100:101], s[0:1], 0, v[16:17]
	v_lshl_add_u64 v[102:103], s[0:1], 0, v[18:19]
	s_mov_b32 s0, 0
	s_mov_b32 s5, 0
	v_mov_b32_e32 v0, 0
	v_mov_b32_e32 v1, v99
	v_mov_b32_e32 v2, v99
	v_mov_b32_e32 v3, v99
	v_mov_b32_e32 v4, v99
	v_mov_b32_e32 v5, v99
	v_mov_b32_e32 v6, v99
	v_mov_b32_e32 v7, v99
	v_mov_b32_e32 v8, v99
	v_mov_b32_e32 v9, v99
	v_mov_b32_e32 v10, v99
	v_mov_b32_e32 v11, v99
	v_mov_b32_e32 v12, v99
	v_mov_b32_e32 v13, v99
	v_mov_b32_e32 v14, v99
	v_mov_b32_e32 v15, v99
	v_mov_b32_e32 v16, 0
	v_mov_b32_e32 v17, v99
	v_mov_b32_e32 v18, v99
	v_mov_b32_e32 v19, v99
	v_mov_b32_e32 v20, v99
	v_mov_b32_e32 v21, v99
	v_mov_b32_e32 v22, v99
	v_mov_b32_e32 v23, v99
	v_mov_b32_e32 v24, v99
	v_mov_b32_e32 v25, v99
	v_mov_b32_e32 v26, v99
	v_mov_b32_e32 v27, v99
	v_mov_b32_e32 v28, v99
	v_mov_b32_e32 v29, v99
	v_mov_b32_e32 v30, v99
	v_mov_b32_e32 v31, v99
	s_waitcnt lgkmcnt(0)
	s_barrier
	v_mad_u32_u24 v156, v105, s42, v176
	v_mad_u32_u24 v157, v105, s42, v176
	v_mad_u32_u24 v188, v107, s42, v98
	v_mad_u32_u24 v189, v108, s42, v98
	v_lshrrev_b32_e32 v111, 1, v98
	v_and_b32_e32 v111, 8, v111
	v_sub_u32_e32 v111, v98, v111
	v_mad_u32_u24 v181, v107, s42, v111
	v_mad_u32_u24 v183, v108, s42, v111
	v_add_u32_e32 v157, 0x9000, v157
	v_add_u32_e32 v181, 0x9000, v181
	v_add_u32_e32 v183, 0x9000, v183
	v_mad_u32_u24 v250, v107, s34, v98
	v_mad_u32_u24 v251, v108, s34, v98
	v_add_u32_e32 v250, 0x4800, v250
	v_add_u32_e32 v251, 0x4800, v251
	ds_read2_b64 v[84:87], v250 offset1:1
	ds_read2_b64 v[80:83], v251 offset1:1
	s_waitcnt lgkmcnt(1)
	ds_write2_b64 v181, v[84:85], v[86:87] offset1:2
	s_waitcnt lgkmcnt(1)
	ds_write2_b64 v183, v[80:81], v[82:83] offset1:2
	s_waitcnt lgkmcnt(0)
	s_barrier
	v_mov_b32_e32 v144, 0
	v_mov_b32_e32 v145, 0
	v_mov_b32_e32 v146, 0
	v_mov_b32_e32 v147, 0
	v_mov_b32_e32 v148, 0
	v_mov_b32_e32 v149, 0
	v_mov_b32_e32 v150, 0
	v_mov_b32_e32 v151, 0
	v_mov_b32_e32 v152, 0
	v_mov_b32_e32 v153, 0
	v_mov_b32_e32 v154, 0
	v_mov_b32_e32 v155, 0
	v_mov_b32_e32 v160, 0
	v_mov_b32_e32 v161, 0
	v_mov_b32_e32 v162, 0
	v_mov_b32_e32 v163, 0
	v_mov_b32_e32 v164, 0
	v_mov_b32_e32 v165, 0
	v_mov_b32_e32 v166, 0
	v_mov_b32_e32 v167, 0
	v_mov_b32_e32 v168, 0
	v_mov_b32_e32 v169, 0
	v_mov_b32_e32 v170, 0
	v_mov_b32_e32 v171, 0
	v_mov_b32_e32 v184, 0
	v_mov_b32_e32 v185, 0
	v_mov_b32_e32 v186, 0
	v_mov_b32_e32 v187, 0
	v_mov_b32_e32 v196, 0
	v_mov_b32_e32 v197, 0
	v_mov_b32_e32 v198, 0
	v_mov_b32_e32 v199, 0
	v_mov_b32_e32 v200, 0
	v_mov_b32_e32 v201, 0
	v_mov_b32_e32 v202, 0
	v_mov_b32_e32 v203, 0
	v_mov_b32_e32 v204, 0
	v_mov_b32_e32 v205, 0
	v_mov_b32_e32 v206, 0
	v_mov_b32_e32 v207, 0
	v_mov_b32_e32 v246, 0
	v_mov_b32_e32 v247, 0
	v_mov_b32_e32 v248, 0
	v_mov_b32_e32 v249, 0
	v_mov_b32_e32 v32, 0xc47a0000
	v_mov_b32_e32 v33, 0xc47a0000
	v_mov_b32_e32 v34, 0xc47a0000
	v_mov_b32_e32 v35, 0xc47a0000
	v_mov_b32_e32 v36, 0xc47a0000
	v_mov_b32_e32 v37, 0xc47a0000
	v_mov_b32_e32 v38, 0xc47a0000
	v_mov_b32_e32 v39, 0xc47a0000
	v_mov_b32_e32 v40, 0xc47a0000
	v_mov_b32_e32 v41, 0xc47a0000
	v_mov_b32_e32 v42, 0xc47a0000
	v_mov_b32_e32 v43, 0xc47a0000
	v_mov_b32_e32 v44, 0xc47a0000
	v_mov_b32_e32 v45, 0xc47a0000
	v_mov_b32_e32 v46, 0xc47a0000
	v_mov_b32_e32 v47, 0xc47a0000
	s_cmp_lt_u32 s5, 3
	s_cselect_b32 s1, 8, 12
	s_cselect_b32 s6, 0x8000, s8
	s_lshl_b32 s1, s12, s1
	s_add_i32 s1, s6, s1
	s_add_i32 s1, s1, s0
	v_add_u32_e32 v111, s1, v110
	v_mad_i64_i32 v[250:251], s[6:7], v111, s43, v[96:97]
	v_add_u32_e32 v111, s1, v109
	global_load_dwordx4 v[92:95], v[250:251], off
	global_load_dwordx4 v[84:87], v[100:101], off
	v_mad_i64_i32 v[250:251], s[6:7], v111, s43, v[96:97]
	s_nop 0
	global_load_dwordx4 v[88:91], v[250:251], off
	global_load_dwordx4 v[80:83], v[102:103], off
	v_lshl_add_u64 v[100:101], v[100:101], 0, s[10:11]
	v_lshl_add_u64 v[102:103], v[102:103], 0, s[10:11]
.Lgq_top:
	s_and_b32 s1, s0, 64
	s_mul_i32 s6, s1, 0x90
	v_add_u32_e32 v159, s6, v156
	v_add_u32_e32 v172, s6, v157
	ds_read_b128 v[112:115], v159
	ds_read_b128 v[116:119], v159 offset:32
	ds_read_b128 v[120:123], v159 offset:64
	ds_read_b128 v[124:127], v159 offset:96
	ds_read_b128 v[128:131], v159 offset:4608
	ds_read_b128 v[132:135], v159 offset:4640
	ds_read_b128 v[136:139], v159 offset:4672
	ds_read_b128 v[140:143], v159 offset:4704
	v_exp_f32_e32 v32, v32
	v_exp_f32_e32 v33, v33
	v_exp_f32_e32 v34, v34
	v_exp_f32_e32 v35, v35
	s_waitcnt lgkmcnt(7)
	v_mfma_f32_32x32x16_bf16 v[48:63], v[112:115], v[76:79], 0
	v_exp_f32_e32 v36, v36
	v_exp_f32_e32 v37, v37
	v_add_f32_e32 v246, v32, v246
	v_add_f32_e32 v247, v33, v247
	v_cvt_pk_bf16_f32 v238, v32, v33
	s_waitcnt lgkmcnt(6)
	v_mfma_f32_32x32x16_bf16 v[48:63], v[116:119], v[72:75], v[48:63]
	v_exp_f32_e32 v38, v38
	v_exp_f32_e32 v39, v39
	v_add_f32_e32 v248, v34, v248
	v_add_f32_e32 v249, v35, v249
	v_cvt_pk_bf16_f32 v239, v34, v35
	s_waitcnt lgkmcnt(5)
	v_mfma_f32_32x32x16_bf16 v[48:63], v[120:123], v[68:71], v[48:63]
	v_exp_f32_e32 v40, v40
	v_exp_f32_e32 v41, v41
	v_add_f32_e32 v246, v36, v246
	v_add_f32_e32 v247, v37, v247
	v_cvt_pk_bf16_f32 v240, v36, v37
	s_waitcnt lgkmcnt(4)
	v_mfma_f32_32x32x16_bf16 v[48:63], v[124:127], v[64:67], v[48:63]
	v_exp_f32_e32 v42, v42
	v_exp_f32_e32 v43, v43
	v_add_f32_e32 v248, v38, v248
	v_add_f32_e32 v249, v39, v249
	v_cvt_pk_bf16_f32 v241, v38, v39
	v_mfma_f32_32x32x16_bf16 v[0:15], v[144:147], v[200:203], v[0:15]
	ds_read_b128 v[144:147], v172
	v_exp_f32_e32 v44, v44
	v_exp_f32_e32 v45, v45
	v_add_f32_e32 v246, v40, v246
	v_add_f32_e32 v247, v41, v247
	v_cvt_pk_bf16_f32 v242, v40, v41
	v_mfma_f32_32x32x16_bf16 v[16:31], v[164:167], v[200:203], v[16:31]
	ds_read_b128 v[164:167], v172 offset:4608
	v_exp_f32_e32 v46, v46
	v_exp_f32_e32 v47, v47
	v_add_f32_e32 v248, v42, v248
	v_add_f32_e32 v249, v43, v249
	v_cvt_pk_bf16_f32 v243, v42, v43
	v_mfma_f32_32x32x16_bf16 v[0:15], v[148:151], v[204:207], v[0:15]
	ds_read_b128 v[148:151], v172 offset:32
	v_add_f32_e32 v246, v44, v246
	v_add_f32_e32 v247, v45, v247
	v_cvt_pk_bf16_f32 v244, v44, v45
	v_add_f32_e32 v248, v46, v248
	v_add_f32_e32 v249, v47, v249
	v_mfma_f32_32x32x16_bf16 v[16:31], v[168:171], v[204:207], v[16:31]
	ds_read_b128 v[168:171], v172 offset:4640
	v_cvt_pk_bf16_f32 v245, v46, v47
	v_exp_f32_e32 v48, v48
	v_exp_f32_e32 v49, v49
	v_exp_f32_e32 v50, v50
	s_waitcnt lgkmcnt(7)
	v_mfma_f32_32x32x16_bf16 v[32:47], v[128:131], v[76:79], 0
	v_exp_f32_e32 v51, v51
	v_exp_f32_e32 v52, v52
	v_add_f32_e32 v246, v48, v246
	v_add_f32_e32 v247, v49, v247
	v_cvt_pk_bf16_f32 v200, v48, v49
	s_waitcnt lgkmcnt(6)
	v_mfma_f32_32x32x16_bf16 v[32:47], v[132:135], v[72:75], v[32:47]
	v_exp_f32_e32 v53, v53
	v_exp_f32_e32 v54, v54
	v_add_f32_e32 v248, v50, v248
	v_add_f32_e32 v249, v51, v249
	v_cvt_pk_bf16_f32 v201, v50, v51
	s_waitcnt lgkmcnt(5)
	v_mfma_f32_32x32x16_bf16 v[32:47], v[136:139], v[68:71], v[32:47]
	v_exp_f32_e32 v55, v55
	v_exp_f32_e32 v56, v56
	v_add_f32_e32 v246, v52, v246
	v_add_f32_e32 v247, v53, v247
	v_cvt_pk_bf16_f32 v202, v52, v53
	s_waitcnt lgkmcnt(4)
	v_mfma_f32_32x32x16_bf16 v[32:47], v[140:143], v[64:67], v[32:47]
	v_exp_f32_e32 v57, v57
	v_exp_f32_e32 v58, v58
	v_add_f32_e32 v248, v54, v248
	v_add_f32_e32 v249, v55, v249
	v_cvt_pk_bf16_f32 v203, v54, v55
	v_mfma_f32_32x32x16_bf16 v[0:15], v[152:155], v[238:241], v[0:15]
	ds_read_b128 v[152:155], v172 offset:64
	v_exp_f32_e32 v59, v59
	v_exp_f32_e32 v60, v60
	v_add_f32_e32 v246, v56, v246
	v_add_f32_e32 v247, v57, v247
	v_cvt_pk_bf16_f32 v204, v56, v57
	v_mfma_f32_32x32x16_bf16 v[16:31], v[184:187], v[238:241], v[16:31]
	ds_read_b128 v[184:187], v172 offset:4672
	v_exp_f32_e32 v61, v61
	v_exp_f32_e32 v62, v62
	v_add_f32_e32 v248, v58, v248
	v_add_f32_e32 v249, v59, v249
	v_cvt_pk_bf16_f32 v205, v58, v59
	v_mfma_f32_32x32x16_bf16 v[0:15], v[160:163], v[242:245], v[0:15]
	ds_read_b128 v[160:163], v172 offset:96
	v_exp_f32_e32 v63, v63
	v_add_f32_e32 v246, v60, v246
	v_add_f32_e32 v247, v61, v247
	v_cvt_pk_bf16_f32 v206, v60, v61
	v_add_f32_e32 v248, v62, v248
	v_mfma_f32_32x32x16_bf16 v[16:31], v[196:199], v[242:245], v[16:31]
	ds_read_b128 v[196:199], v172 offset:4704
	v_add_f32_e32 v249, v63, v249
	v_cvt_pk_bf16_f32 v207, v62, v63
	s_cmpk_eq_i32 s0, 0x10c0
	s_cbranch_scc1 .Lgq_nostore
	s_and_b32 s1, s0, 64
	s_xor_b32 s1, s1, 64
	s_mul_i32 s6, s1, 0x90
	v_add_u32_e32 v111, s6, v188
	v_add_u32_e32 v250, s6, v181
	v_add_u32_e32 v251, s6, v189
	v_add_u32_e32 v237, s6, v183
	s_waitcnt vmcnt(3)
	ds_write_b128 v111, v[92:95]
	s_waitcnt vmcnt(2)
	ds_write2_b64 v250, v[84:85], v[86:87] offset1:2
	s_waitcnt vmcnt(1)
	ds_write_b128 v251, v[88:91]
	s_waitcnt vmcnt(0)
	ds_write2_b64 v237, v[80:81], v[82:83] offset1:2
.Lgq_nostore:
	s_add_i32 s0, s0, 64
	s_add_i32 s5, s5, 1
	s_cmpk_ge_i32 s0, 0x10c0
	s_cbranch_scc1 .Lgq_noload
	s_cmp_lt_u32 s5, 3
	s_cselect_b32 s1, 8, 12
	s_cselect_b32 s6, 0x8000, s8
	s_lshl_b32 s1, s12, s1
	s_add_i32 s1, s6, s1
	s_add_i32 s1, s1, s0
	v_add_u32_e32 v111, s1, v110
	v_mad_i64_i32 v[250:251], s[6:7], v111, s43, v[96:97]
	v_add_u32_e32 v111, s1, v109
	global_load_dwordx4 v[92:95], v[250:251], off
	global_load_dwordx4 v[84:87], v[100:101], off
	v_mad_i64_i32 v[250:251], s[6:7], v111, s43, v[96:97]
	s_nop 0
	global_load_dwordx4 v[88:91], v[250:251], off
	global_load_dwordx4 v[80:83], v[102:103], off
	v_lshl_add_u64 v[100:101], v[100:101], 0, s[10:11]
	v_lshl_add_u64 v[102:103], v[102:103], 0, s[10:11]
.Lgq_noload:
	s_waitcnt lgkmcnt(0)
	s_barrier
	s_cmpk_lg_i32 s0, 0x1100
	s_cbranch_scc1 .Lgq_top
	v_exp_f32_e32 v32, v32
	v_exp_f32_e32 v33, v33
	v_exp_f32_e32 v34, v34
	v_exp_f32_e32 v35, v35
	v_exp_f32_e32 v36, v36
	v_exp_f32_e32 v37, v37
	v_add_f32_e32 v246, v32, v246
	v_add_f32_e32 v247, v33, v247
	v_cvt_pk_bf16_f32 v238, v32, v33
	v_exp_f32_e32 v38, v38
	v_exp_f32_e32 v39, v39
	v_add_f32_e32 v248, v34, v248
	v_add_f32_e32 v249, v35, v249
	v_cvt_pk_bf16_f32 v239, v34, v35
	v_exp_f32_e32 v40, v40
	v_exp_f32_e32 v41, v41
	v_add_f32_e32 v246, v36, v246
	v_add_f32_e32 v247, v37, v247
	v_cvt_pk_bf16_f32 v240, v36, v37
	v_exp_f32_e32 v42, v42
	v_exp_f32_e32 v43, v43
	v_add_f32_e32 v248, v38, v248
	v_add_f32_e32 v249, v39, v249
	v_cvt_pk_bf16_f32 v241, v38, v39
	v_exp_f32_e32 v44, v44
	v_exp_f32_e32 v45, v45
	v_add_f32_e32 v246, v40, v246
	v_add_f32_e32 v247, v41, v247
	v_cvt_pk_bf16_f32 v242, v40, v41
	v_exp_f32_e32 v46, v46
	v_exp_f32_e32 v47, v47
	v_add_f32_e32 v248, v42, v248
	v_add_f32_e32 v249, v43, v249
	v_cvt_pk_bf16_f32 v243, v42, v43
	v_add_f32_e32 v246, v44, v246
	v_add_f32_e32 v247, v45, v247
	v_cvt_pk_bf16_f32 v244, v44, v45
	v_add_f32_e32 v248, v46, v248
	v_add_f32_e32 v249, v47, v249
	v_cvt_pk_bf16_f32 v245, v46, v47
	s_nop 1
	v_mfma_f32_32x32x16_bf16 v[0:15], v[144:147], v[200:203], v[0:15]
	v_mfma_f32_32x32x16_bf16 v[16:31], v[164:167], v[200:203], v[16:31]
	v_mfma_f32_32x32x16_bf16 v[0:15], v[148:151], v[204:207], v[0:15]
	v_mfma_f32_32x32x16_bf16 v[16:31], v[168:171], v[204:207], v[16:31]
	v_mfma_f32_32x32x16_bf16 v[0:15], v[152:155], v[238:241], v[0:15]
	v_mfma_f32_32x32x16_bf16 v[16:31], v[184:187], v[238:241], v[16:31]
	v_mfma_f32_32x32x16_bf16 v[0:15], v[160:163], v[242:245], v[0:15]
	v_mfma_f32_32x32x16_bf16 v[16:31], v[196:199], v[242:245], v[16:31]
	v_add_f32_e32 v246, v246, v247
	v_add_f32_e32 v248, v248, v249
	s_nop 1
	v_add_f32_e32 v246, v246, v248
	s_nop 1
	v_add_f32_e32 v32, v99, v246
	s_nop 7
	s_nop 7
	ds_bpermute_b32 v35, v231, v32
	v_mov_b32_e32 v33, v179
	s_waitcnt lgkmcnt(0)
	s_barrier
	v_add_f32_e32 v32, v32, v35
	v_div_scale_f32 v35, s[0:1], v32, v32, 1.0
	v_rcp_f32_e32 v36, v35
	s_add_i32 s5, s3, 0x100
	v_ashrrev_i32_e32 v34, 1, v33
	v_fma_f32 v37, -v35, v36, 1.0
	v_fmac_f32_e32 v36, v37, v36
	v_div_scale_f32 v37, vcc, 1.0, v32, 1.0
	v_mul_f32_e32 v38, v37, v36
	v_fma_f32 v39, -v35, v38, v37
	v_fmac_f32_e32 v38, v39, v36
	v_add_u32_e32 v34, s4, v34
	v_fma_f32 v35, -v35, v38, v37
	v_div_fmas_f32 v35, v35, v36, v38
	v_ashrrev_i32_e32 v34, 5, v34
	v_div_fixup_f32 v32, v35, v32, 1.0
	v_ashrrev_i32_e32 v35, 31, v34
	v_lshlrev_b64 v[34:35], 16, v[34:35]
	s_lshr_b32 s96, s5, 4
	v_lshl_add_u64 v[34:35], s[64:65], 0, v[34:35]
	v_pk_mul_f32 v[0:1], v[0:1], v[32:33] op_sel_hi:[1,0]
	v_pk_mul_f32 v[2:3], v[2:3], v[32:33] op_sel_hi:[1,0]
	s_lshl_b64 s[0:1], s[96:97], 10
	v_lshlrev_b32_e32 v36, 4, v33
	v_cvt_pk_bf16_f32 v0, v0, v1
	v_cvt_pk_bf16_f32 v1, v2, v3
	v_lshl_add_u64 v[2:3], v[34:35], 0, s[0:1]
	v_and_b32_e32 v176, 0x1f0, v36
	v_lshrrev_b32_e32 v33, 2, v33
	v_lshl_add_u64 v[2:3], v[2:3], 0, v[176:177]
	v_and_b32_e32 v36, 8, v33
	v_mov_b32_e32 v37, v177
	s_add_i32 s0, s3, 0x108
	v_lshl_add_u64 v[2:3], v[2:3], 0, v[36:37]
	s_lshr_b32 s96, s0, 4
	global_store_dwordx2 v[2:3], v[0:1], off
	v_pk_mul_f32 v[0:1], v[4:5], v[32:33] op_sel_hi:[1,0]
	v_pk_mul_f32 v[2:3], v[6:7], v[32:33] op_sel_hi:[1,0]
	s_lshl_b64 s[0:1], s[96:97], 10
	v_cvt_pk_bf16_f32 v0, v0, v1
	v_cvt_pk_bf16_f32 v1, v2, v3
	v_lshl_add_u64 v[2:3], v[34:35], 0, s[0:1]
	v_lshl_add_u64 v[2:3], v[2:3], 0, v[176:177]
	s_add_i32 s0, s3, 0x110
	v_lshl_add_u64 v[2:3], v[2:3], 0, v[36:37]
	s_lshr_b32 s96, s0, 4
	global_store_dwordx2 v[2:3], v[0:1], off offset:512
	v_pk_mul_f32 v[0:1], v[8:9], v[32:33] op_sel_hi:[1,0]
	v_pk_mul_f32 v[2:3], v[10:11], v[32:33] op_sel_hi:[1,0]
	s_lshl_b64 s[0:1], s[96:97], 10
	v_cvt_pk_bf16_f32 v0, v0, v1
	v_cvt_pk_bf16_f32 v1, v2, v3
	v_lshl_add_u64 v[2:3], v[34:35], 0, s[0:1]
	v_lshl_add_u64 v[2:3], v[2:3], 0, v[176:177]
	s_add_i32 s0, s3, 0x118
	v_lshl_add_u64 v[2:3], v[2:3], 0, v[36:37]
	s_lshr_b32 s96, s0, 4
	global_store_dwordx2 v[2:3], v[0:1], off
	v_pk_mul_f32 v[0:1], v[12:13], v[32:33] op_sel_hi:[1,0]
	v_pk_mul_f32 v[2:3], v[14:15], v[32:33] op_sel_hi:[1,0]
	s_lshl_b64 s[0:1], s[96:97], 10
	v_cvt_pk_bf16_f32 v0, v0, v1
	v_cvt_pk_bf16_f32 v1, v2, v3
	v_lshl_add_u64 v[2:3], v[34:35], 0, s[0:1]
	v_lshl_add_u64 v[2:3], v[2:3], 0, v[176:177]
	s_add_i32 s0, s3, 0x120
	v_lshl_add_u64 v[2:3], v[2:3], 0, v[36:37]
	s_lshr_b32 s96, s0, 4
	global_store_dwordx2 v[2:3], v[0:1], off offset:512
	v_pk_mul_f32 v[0:1], v[16:17], v[32:33] op_sel_hi:[1,0]
	v_pk_mul_f32 v[2:3], v[18:19], v[32:33] op_sel_hi:[1,0]
	s_lshl_b64 s[0:1], s[96:97], 10
	v_cvt_pk_bf16_f32 v0, v0, v1
	v_cvt_pk_bf16_f32 v1, v2, v3
	v_lshl_add_u64 v[2:3], v[34:35], 0, s[0:1]
	v_lshl_add_u64 v[2:3], v[2:3], 0, v[176:177]
	s_add_i32 s0, s3, 0x128
	v_lshl_add_u64 v[2:3], v[2:3], 0, v[36:37]
	s_lshr_b32 s96, s0, 4
	global_store_dwordx2 v[2:3], v[0:1], off
	v_pk_mul_f32 v[0:1], v[20:21], v[32:33] op_sel_hi:[1,0]
	v_pk_mul_f32 v[2:3], v[22:23], v[32:33] op_sel_hi:[1,0]
	s_lshl_b64 s[0:1], s[96:97], 10
	v_cvt_pk_bf16_f32 v0, v0, v1
	v_cvt_pk_bf16_f32 v1, v2, v3
	v_lshl_add_u64 v[2:3], v[34:35], 0, s[0:1]
	v_lshl_add_u64 v[2:3], v[2:3], 0, v[176:177]
	s_add_i32 s0, s3, 0x130
	v_lshl_add_u64 v[2:3], v[2:3], 0, v[36:37]
	s_lshr_b32 s96, s0, 4
	global_store_dwordx2 v[2:3], v[0:1], off offset:512
	v_pk_mul_f32 v[0:1], v[24:25], v[32:33] op_sel_hi:[1,0]
	v_pk_mul_f32 v[2:3], v[26:27], v[32:33] op_sel_hi:[1,0]
	s_lshl_b64 s[0:1], s[96:97], 10
	v_cvt_pk_bf16_f32 v0, v0, v1
	v_cvt_pk_bf16_f32 v1, v2, v3
	v_lshl_add_u64 v[2:3], v[34:35], 0, s[0:1]
	v_lshl_add_u64 v[2:3], v[2:3], 0, v[176:177]
	s_addk_i32 s3, 0x138
	v_lshl_add_u64 v[2:3], v[2:3], 0, v[36:37]
	s_lshr_b32 s96, s3, 4
	global_store_dwordx2 v[2:3], v[0:1], off
	v_pk_mul_f32 v[0:1], v[28:29], v[32:33] op_sel_hi:[1,0]
	v_pk_mul_f32 v[2:3], v[30:31], v[32:33] op_sel_hi:[1,0]
	s_lshl_b64 s[0:1], s[96:97], 10
	v_cvt_pk_bf16_f32 v0, v0, v1
	v_cvt_pk_bf16_f32 v1, v2, v3
	v_lshl_add_u64 v[2:3], v[34:35], 0, s[0:1]
	v_lshl_add_u64 v[2:3], v[2:3], 0, v[176:177]
	v_lshl_add_u64 v[2:3], v[2:3], 0, v[36:37]
	global_store_dwordx2 v[2:3], v[0:1], off offset:512
